# static s_setprio 1 for waves 4-7 also around the attention unit loop
# baseline (speedup 1.0000x reference)
.LBB0_238:
	v_writelane_b32 v255, s72, 21
	s_nop 1
	v_writelane_b32 v255, s73, 22
	s_or_b64 exec, exec, s[0:1]
	s_cmpk_lt_i32 s87, 0x3e8
	s_mov_b64 s[6:7], -1
	s_waitcnt lgkmcnt(0)
	s_barrier
	s_cbranch_scc0 .LBB0_394
	v_readlane_b32 s6, v253, 44
	s_mov_b64 s[4:5], s[92:93]
	s_mov_b64 s[0:1], s[94:95]
	v_mov_b32_e32 v0, v193
	v_readlane_b32 s4, v254, 29
	v_readlane_b32 s5, v254, 30
	v_writelane_b32 v255, s87, 23
	s_mov_b32 s57, s97
	s_mov_b32 s56, s96
	s_andn2_b64 vcc, exec, s[4:5]
	v_readfirstlane_b32 s46, v0
	s_cbranch_vccnz .LBB0_246
	s_lshl_b32 s4, s38, 6
	s_mov_b32 s5, s39
	v_readlane_b32 s8, v253, 0
	s_ashr_i32 s2, s46, 6
	s_lshl_b64 s[4:5], s[4:5], 2
	v_readlane_b32 s22, v253, 14
	v_readlane_b32 s23, v253, 15
	s_add_u32 s4, s22, s4
	v_readlane_b32 s9, v253, 1
	v_readlane_b32 s10, v253, 2
	v_readlane_b32 s11, v253, 3
	v_readlane_b32 s12, v253, 4
	v_readlane_b32 s13, v253, 5
	v_readlane_b32 s14, v253, 6
	v_readlane_b32 s15, v253, 7
	s_addc_u32 s5, s23, s5
	s_lshl_b32 s38, s38, 5
	s_lshl_b64 s[6:7], s[38:39], 2
	v_readlane_b32 s8, v253, 17
	v_readlane_b32 s9, v253, 18
	s_add_u32 s38, s8, s6
	v_writelane_b32 v255, s2, 17
	s_addc_u32 s2, s9, s7
	s_add_u32 s6, s0, 0x23400000
	v_and_b32_e32 v5, 64, v236
	v_writelane_b32 v255, s2, 19
	s_addc_u32 s7, s1, 0
	v_xor_b32_e32 v4, 1, v236
	v_add_u32_e32 v5, 64, v5
	v_ashrrev_i32_e32 v1, 1, v0
	v_writelane_b32 v255, s6, 24
	v_cmp_lt_i32_e32 vcc, v4, v5
	v_lshrrev_b32_e32 v8, 1, v1
	v_writelane_b32 v255, s7, 25
	v_cndmask_b32_e32 v4, v236, v4, vcc
	s_movk_i32 s6, 0x90
	v_add_u32_e32 v138, 0xffffff80, v1
	v_lshlrev_b32_e32 v139, 2, v4
	v_mul_lo_u32 v4, v1, s6
	v_and_b32_e32 v7, 8, v0
	v_and_b32_e32 v8, 4, v8
	v_and_b32_e32 v1, 0x7ffffff3, v1
	v_or3_b32 v1, v1, v7, v8
	v_xor_b32_e32 v8, 32, v236
	v_and_b32_e32 v3, 1, v0
	v_bfe_u32 v7, v0, 5, 1
	v_and_b32_e32 v0, 31, v0
	v_cmp_lt_i32_e32 vcc, v8, v5
	s_movk_i32 s2, 0x80
	v_lshlrev_b32_e32 v160, 5, v7
	v_cndmask_b32_e32 v5, v236, v8, vcc
	v_or_b32_e32 v8, 0x80, v0
	v_mad_i32_i24 v9, v7, -4, v8
	v_cmp_gt_u32_e64 s[8:9], s2, v9
	v_mad_i32_i24 v9, v7, -4, -1
	v_add_u32_e32 v10, v9, v8
	v_writelane_b32 v255, s8, 26
	v_readlane_b32 s18, v253, 10
	v_readlane_b32 s19, v253, 11
	v_writelane_b32 v255, s9, 27
	v_cmp_gt_u32_e64 s[8:9], s2, v10
	v_mad_i32_i24 v10, v7, -4, -2
	v_add_u32_e32 v11, v10, v8
	v_writelane_b32 v255, s8, 28
	v_lshl_add_u64 v[124:125], s[4:5], 0, v[160:161]
	v_lshlrev_b32_e32 v160, 7, v3
	v_writelane_b32 v255, s9, 29
	v_cmp_gt_u32_e64 s[8:9], s2, v11
	v_mad_i32_i24 v11, v7, -4, -3
	v_add_u32_e32 v12, v11, v8
	v_writelane_b32 v255, s8, 30
	v_lshl_add_u64 v[126:127], s[18:19], 0, v[160:161]
	v_lshlrev_b32_e32 v2, 5, v3
	v_writelane_b32 v255, s9, 31
	v_cmp_gt_u32_e64 s[8:9], s2, v12
	v_mad_i32_i24 v12, v7, -4, -8
	v_add_u32_e32 v13, v12, v8
	v_writelane_b32 v255, s8, 32
	v_lshlrev_b32_e32 v1, 1, v1
	v_lshlrev_b32_e32 v6, 6, v3
	v_writelane_b32 v255, s9, 33
	v_cmp_gt_u32_e64 s[8:9], s2, v13
	v_mad_i32_i24 v13, v7, -4, -9
	v_add_u32_e32 v14, v13, v8
	v_writelane_b32 v255, s8, 34
	v_lshlrev_b32_e32 v140, 2, v5
	v_mul_u32_u24_e32 v5, 0x210, v0
	v_writelane_b32 v255, s9, 35
	v_cmp_gt_u32_e64 s[8:9], s2, v14
	v_mad_i32_i24 v14, v7, -4, -10
	v_add_u32_e32 v15, v14, v8
	v_writelane_b32 v255, s8, 36
	s_mov_b32 s4, 0x9000
	v_readlane_b32 s54, v253, 41
	v_writelane_b32 v255, s9, 37
	v_cmp_gt_u32_e64 s[8:9], s2, v15
	v_mad_i32_i24 v15, v7, -4, -11
	v_add_u32_e32 v16, v15, v8
	v_writelane_b32 v255, s8, 38
	s_andn2_b32 s46, s46, 63
	v_lshlrev_b32_e32 v132, 1, v2
	v_writelane_b32 v255, s9, 39
	v_cmp_gt_u32_e64 s[8:9], s2, v16
	v_mad_i32_i24 v16, v7, -4, -16
	v_add_u32_e32 v17, v16, v8
	v_writelane_b32 v255, s8, 40
	v_add_u32_e32 v150, v4, v6
	s_mov_b32 s47, s54
	v_writelane_b32 v255, s9, 41
	v_cmp_gt_u32_e64 s[8:9], s2, v17
	v_not_b32_e32 v17, 16
	v_mad_i32_i24 v17, v7, -4, v17
	v_writelane_b32 v255, s8, 42
	v_add_u32_e32 v18, v17, v8
	v_readlane_b32 s16, v253, 8
	v_writelane_b32 v255, s9, 43
	v_cmp_gt_u32_e64 s[8:9], s2, v18
	v_not_b32_e32 v18, 17
	v_mad_i32_i24 v18, v7, -4, v18
	v_writelane_b32 v255, s8, 44
	v_add_u32_e32 v19, v18, v8
	v_readlane_b32 s17, v253, 9
	v_writelane_b32 v255, s9, 45
	v_cmp_gt_u32_e64 s[8:9], s2, v19
	v_not_b32_e32 v19, 18
	v_mad_i32_i24 v19, v7, -4, v19
	v_writelane_b32 v255, s8, 46
	v_add_u32_e32 v20, v19, v8
	v_readlane_b32 s20, v253, 12
	v_writelane_b32 v255, s9, 47
	v_cmp_gt_u32_e64 s[8:9], s2, v20
	v_not_b32_e32 v20, 23
	v_mad_i32_i24 v20, v7, -4, v20
	v_add_u32_e32 v21, v20, v8
	v_cmp_gt_u32_e64 s[58:59], s2, v21
	v_not_b32_e32 v21, 24
	v_mad_i32_i24 v21, v7, -4, v21
	v_add_u32_e32 v22, v21, v8
	v_cmp_gt_u32_e64 s[60:61], s2, v22
	v_not_b32_e32 v22, 25
	v_mad_i32_i24 v22, v7, -4, v22
	v_add_u32_e32 v23, v22, v8
	v_cmp_gt_u32_e64 s[62:63], s2, v23
	v_not_b32_e32 v23, 26
	v_mad_i32_i24 v23, v7, -4, v23
	v_add_u32_e32 v8, v23, v8
	v_cmp_gt_u32_e64 s[64:65], s2, v8
	v_mad_i32_i24 v8, v7, -4, v0
	v_cmp_gt_u32_e64 s[66:67], s2, v8
	v_add_u32_e32 v8, v9, v0
	v_cmp_gt_u32_e64 s[68:69], s2, v8
	v_add_u32_e32 v8, v10, v0
	v_cmp_gt_u32_e64 s[70:71], s2, v8
	v_add_u32_e32 v8, v11, v0
	v_cmp_gt_u32_e64 s[72:73], s2, v8
	v_add_u32_e32 v8, v12, v0
	v_cmp_gt_u32_e64 s[74:75], s2, v8
	v_add_u32_e32 v8, v13, v0
	v_cmp_gt_u32_e64 s[76:77], s2, v8
	v_add_u32_e32 v8, v14, v0
	v_cmp_gt_u32_e64 s[78:79], s2, v8
	v_add_u32_e32 v8, v15, v0
	v_lshlrev_b32_e32 v9, 4, v7
	v_lshlrev_b32_e32 v10, 12, v0
	v_cmp_gt_u32_e64 s[80:81], s2, v8
	v_add_u32_e32 v8, v16, v0
	v_or_b32_e32 v160, v10, v9
	v_cmp_gt_u32_e64 s[82:83], s2, v8
	v_add_u32_e32 v8, v17, v0
	v_lshl_add_u64 v[128:129], s[0:1], 0, v[160:161]
	v_lshl_or_b32 v160, v7, 3, v10
	v_cmp_gt_u32_e64 s[84:85], s2, v8
	v_add_u32_e32 v8, v18, v0
	v_lshl_add_u64 v[130:131], s[0:1], 0, v[160:161]
	s_movk_i32 s0, 0x4200
	v_cmp_gt_u32_e64 s[86:87], s2, v8
	v_add_u32_e32 v8, v19, v0
	v_or_b32_e32 v12, 2, v2
	v_mad_u32_u24 v141, v3, s0, v1
	s_movk_i32 s0, 0x210
	v_writelane_b32 v255, s8, 48
	v_cmp_gt_u32_e64 s[88:89], s2, v8
	v_add_u32_e32 v7, v20, v0
	v_add_u32_e32 v8, v21, v0
	v_add_u32_e32 v10, v22, v0
	v_add_u32_e32 v11, v23, v0
	v_mad_u32_u24 v142, v12, s0, v1
	v_writelane_b32 v255, s9, 49
	v_add_u32_e32 v143, 0x420, v142
	v_add_u32_e32 v144, 0x840, v142
	v_add_u32_e32 v145, 0xc60, v142
	v_add_u32_e32 v146, 0x1ce0, v142
	v_add_u32_e32 v147, 0x2d60, v142
	v_add3_u32 v148, v5, v9, s4
	v_mad_u32_u24 v149, v0, s6, v9
	v_cmp_gt_u32_e64 s[90:91], s2, v7
	v_cmp_gt_u32_e64 s[92:93], s2, v8
	v_cmp_gt_u32_e64 s[94:95], s2, v10
	v_cmp_gt_u32_e64 s[96:97], s2, v11
	s_movk_i32 s2, 0x61
	v_readlane_b32 s21, v253, 13
	v_readlane_b32 s10, v253, 19
	v_readlane_b32 s11, v253, 20
	v_readlane_b32 s12, v253, 21
	v_readlane_b32 s13, v253, 22
	v_readlane_b32 s14, v253, 23
	v_readlane_b32 s15, v253, 24
	v_readfirstlane_b32 s32, v193
	s_nop 3
	s_lshr_b32 s32, s32, 6
	s_cmp_ge_u32 s32, 4
	s_cbranch_scc0 .Lmy_prio_at
	s_setprio 1
.Lmy_prio_at:
.LBB0_241:
	s_ashr_i32 s36, s54, 2
	v_lshl_add_u32 v160, s36, 7, v138
	s_and_b32 s4, s54, 3
	v_cmp_lt_i32_e32 vcc, -1, v160
	v_mov_b32_e32 v24, 0
	s_mov_b32 s55, 0
	v_mov_b32_e32 v12, 0
	v_mov_b32_e32 v13, 0
	v_mov_b32_e32 v14, 0
	v_mov_b32_e32 v15, 0
	v_mov_b32_e32 v4, 0
	v_mov_b32_e32 v5, 0
	v_mov_b32_e32 v6, 0
	v_mov_b32_e32 v7, 0
	v_mov_b32_e32 v8, 0
	v_mov_b32_e32 v9, 0
	v_mov_b32_e32 v10, 0
	v_mov_b32_e32 v11, 0
	v_mov_b32_e32 v0, 0
	v_mov_b32_e32 v1, 0
	v_mov_b32_e32 v2, 0
	v_mov_b32_e32 v3, 0
	v_mov_b32_e32 v25, 0
	v_mov_b32_e32 v26, 0
	v_mov_b32_e32 v27, 0
	v_mov_b32_e32 v28, 0
	v_mov_b32_e32 v29, 0
	v_mov_b32_e32 v30, 0
	v_mov_b32_e32 v31, 0
	v_mov_b32_e32 v16, 0
	v_mov_b32_e32 v17, 0
	v_mov_b32_e32 v18, 0
	v_mov_b32_e32 v19, 0
	v_mov_b32_e32 v20, 0
	v_mov_b32_e32 v21, 0
	v_mov_b32_e32 v22, 0
	v_mov_b32_e32 v23, 0
	s_and_saveexec_b64 s[0:1], vcc
	s_cbranch_execz .LBB0_243
	v_readlane_b32 s6, v255, 24
	v_lshlrev_b64 v[0:1], 10, v[160:161]
	v_readlane_b32 s7, v255, 25
	s_mov_b32 s5, s38
	s_lshl_b32 s38, s4, 7
	v_lshl_add_u64 v[0:1], s[6:7], 0, v[0:1]
	v_lshl_add_u64 v[0:1], v[0:1], 0, s[38:39]
	v_mov_b32_e32 v133, v161
	v_lshl_add_u64 v[0:1], v[0:1], 0, v[132:133]
	flat_load_dwordx4 v[24:27], v[0:1]
	flat_load_dwordx4 v[28:31], v[0:1] offset:16
	flat_load_dwordx4 v[12:15], v[0:1] offset:512
	flat_load_dwordx4 v[4:7], v[0:1] offset:528
	flat_load_dwordx4 v[16:19], v[0:1] offset:32
	flat_load_dwordx4 v[20:23], v[0:1] offset:48
	flat_load_dwordx4 v[8:11], v[0:1] offset:544
	s_nop 0
	flat_load_dwordx4 v[0:3], v[0:1] offset:560
	s_mov_b32 s38, s5

.LBB0_246:
	s_setprio 0
	s_waitcnt vmcnt(0)
	v_mov_b32_e32 v0, v193
	s_barrier
	s_nop 0
	v_cmp_eq_u32_e32 vcc, 0, v0
	s_mov_b64 s[0:1], exec
	v_readlane_b32 s88, v253, 17
	v_readlane_b32 s90, v253, 19
	v_readlane_b32 s91, v253, 20
	s_mov_b32 s96, s56
	s_mov_b32 s97, s57
	v_readlane_b32 s78, v254, 53
	v_readlane_b32 s80, v254, 55
	v_readlane_b32 s82, v254, 57
	v_readlane_b32 s84, v254, 59
	v_readlane_b32 s90, v254, 61
	v_readlane_b32 s30, v254, 63
	v_readlane_b32 s44, v255, 1
	v_readlane_b32 s46, v255, 3
	v_readlane_b32 s56, v255, 5
	v_readlane_b32 s54, v255, 7
	v_readlane_b32 s68, v255, 9
	v_readlane_b32 s70, v255, 11
	v_readlane_b32 s58, v255, 13
	s_and_b64 s[4:5], s[0:1], vcc
	v_readlane_b32 s89, v253, 18
	v_readlane_b32 s92, v253, 21
	v_readlane_b32 s93, v253, 22
	v_readlane_b32 s94, v253, 23
	v_readlane_b32 s95, v253, 24
	v_readlane_b32 s79, v254, 54
	v_readlane_b32 s81, v254, 56
	v_readlane_b32 s83, v254, 58
	v_readlane_b32 s85, v254, 60
	v_readlane_b32 s91, v254, 62
	v_readlane_b32 s31, v255, 0
	v_readlane_b32 s45, v255, 2
	v_readlane_b32 s47, v255, 4
	v_readlane_b32 s57, v255, 6
	v_readlane_b32 s55, v255, 8
	v_readlane_b32 s69, v255, 10
	v_readlane_b32 s71, v255, 12
	v_readlane_b32 s59, v255, 14
	s_mov_b32 s75, 0xfffe0
	v_readlane_b32 s19, v255, 23
	s_mov_b64 exec, s[4:5]
	s_cbranch_execz .LBB0_298
	v_mov_b32_e32 v0, 0x23fc0
	s_waitcnt vmcnt(0) expcnt(0) lgkmcnt(0)
	ds_read_b32 v2, v0
	ds_read_b32 v0, v252
	s_waitcnt lgkmcnt(1)
	v_cmp_ne_u32_e32 vcc, 0, v2
	s_cbranch_vccnz .LBB0_262
	s_mov_b32 s10, 1
	s_branch .LBB0_250
